# baseline (speedup 1.0000x reference)
; __device__ __forceinline__ char* wsp() { return (char*)inp(48); }
; __device__ __forceinline__ int otid() { int t = threadIdx.x; asm volatile("" : "+v"(t)); return t; }
; __device__ __forceinline__ void norm_phase(const float* __restrict__ x, const float* __restrict__ w, u16* __restrict__ out, int mode) {
;   const int tid_ = otid(); const int wid = tid_ >> 6, lane = tid_ & 63;
;   f32x4 v[8], nv[8];
;   int row = blockIdx.x * 8 + wid;
;   if (row < NTOK) {
; #pragma unroll
;     for (int it = 0; it < 8; ++it) v[it] = *(const f32x4*)(x + (long)row * DM + it * 256 + lane * 4);
;   }
;   for (; row < NTOK; row += gridDim.x * 8) {
;     const int nrow = row + gridDim.x * 8;
;     if (nrow < NTOK) {
; #pragma unroll
;       for (int it = 0; it < 8; ++it) nv[it] = *(const f32x4*)(x + (long)nrow * DM + it * 256 + lane * 4);
;     }
;     float ss = 0.f;
; #pragma unroll
;     for (int it = 0; it < 8; ++it) ss += v[it][0] * v[it][0] + v[it][1] * v[it][1] + v[it][2] * v[it][2] + v[it][3] * v[it][3];
;     ss = wave_sum(ss);
; __global__ void __launch_bounds__(512, 2) fwd_megakernel(Params P) {
;     ...
;   for (int g = blockIdx.x; g < 128; g += gridDim.x) s5_prep_group(P, g, shm);
;   if (blockIdx.x == 0) { if (threadIdx.x == 0) *(unsigned*)(wsp() + OFF_MISC + 65536) = 0u;
;     for (int i = threadIdx.x; i < XCD_BAR_WORDS; i += 512) ((unsigned*)(wsp() + OFF_MISC + 131072))[i] = 0u; }
;   norm_phase(inp(0), inp(1), A1, 0);
.LBB0_171:
	s_mov_b32 s10, 1
	s_mov_b32 s8, 48
	v_mov_b32_e32 v1, v150
	s_lshl_b32 s4, s62, 3
	v_ashrrev_i32_e32 v2, 6, v1
	s_add_i32 s12, s4, 0xfffffc00
	s_cmpk_lt_i32 s62, 0x80
	s_cselect_b32 s12, 0x4000, s12
	v_add_u32_e32 v82, s12, v2
	s_movk_i32 s12, 0x4000
	v_writelane_b32 v255, s4, 5
	v_cmp_gt_i32_e32 vcc, s12, v82
	v_mbcnt_lo_u32_b32 v88, -1, 0
	s_and_saveexec_b64 s[4:5], vcc
	s_cbranch_execz .LBB0_176
	s_ashr_i32 s7, s6, 31
	s_lshl_b64 s[6:7], s[6:7], 3
	s_add_u32 s14, s0, s6
	s_addc_u32 s15, s1, s7
	s_ashr_i32 s11, s10, 31
	s_lshl_b64 s[6:7], s[10:11], 3
	s_add_u32 s10, s0, s6
	s_addc_u32 s11, s1, s7
	s_ashr_i32 s9, s8, 31
	s_lshl_b64 s[6:7], s[8:9], 3
	s_add_u32 s16, s0, s6
	s_addc_u32 s17, s1, s7
	s_load_dwordx2 s[18:19], s[14:15], 0x0
	s_load_dwordx2 s[8:9], s[10:11], 0x0
	s_load_dwordx2 s[6:7], s[16:17], 0x0
	v_ashrrev_i32_e32 v83, 31, v82
	v_lshlrev_b32_e32 v1, 2, v1
	v_lshlrev_b64 v[2:3], 13, v[82:83]
	v_and_b32_e32 v30, 0xfc, v1
	s_waitcnt lgkmcnt(0)
	v_lshl_add_u64 v[2:3], s[18:19], 0, v[2:3]
	v_lshlrev_b32_e32 v26, 2, v30
	v_mov_b32_e32 v27, 0
	v_lshl_add_u64 v[2:3], v[2:3], 0, v[26:27]
	s_movk_i32 s10, 0x1000
	v_add_co_u32_e32 v28, vcc, s10, v2
	global_load_dwordx4 v[66:69], v[2:3], off
	global_load_dwordx4 v[62:65], v[2:3], off offset:1024
	global_load_dwordx4 v[58:61], v[2:3], off offset:2048
	global_load_dwordx4 v[22:25], v[2:3], off offset:3072
	v_addc_co_u32_e32 v29, vcc, 0, v3, vcc
	global_load_dwordx4 v[18:21], v[28:29], off
	global_load_dwordx4 v[14:17], v[28:29], off offset:1024
	global_load_dwordx4 v[10:13], v[28:29], off offset:2048
	global_load_dwordx4 v[2:5], v[28:29], off offset:3072
	global_load_dwordx4 v[6:9], v26, s[8:9]
	v_mbcnt_hi_u32_b32 v28, -1, v88
	v_and_b32_e32 v1, 64, v28
	v_add_u32_e32 v29, 64, v1
	v_xor_b32_e32 v1, 32, v28
	v_cmp_lt_i32_e32 vcc, v1, v29
	v_xor_b32_e32 v31, 16, v28
	v_lshl_add_u64 v[70:71], s[18:19], 0, v[26:27]
	v_cndmask_b32_e32 v1, v28, v1, vcc
	v_cmp_lt_i32_e32 vcc, v31, v29
	v_lshl_add_u64 v[72:73], s[8:9], 0, v[26:27]
	s_add_i32 s13, s22, 0xffffff80
	s_lshl_b32 s13, s13, 3
	v_cndmask_b32_e32 v31, v28, v31, vcc
	v_lshlrev_b32_e32 v89, 2, v31
	v_xor_b32_e32 v31, 8, v28
	v_cmp_lt_i32_e32 vcc, v31, v29
	v_lshlrev_b32_e32 v1, 2, v1
	s_movk_i32 s14, 0x3fff
	v_cndmask_b32_e32 v31, v28, v31, vcc
	v_lshlrev_b32_e32 v90, 2, v31
	v_xor_b32_e32 v31, 4, v28
	v_cmp_lt_i32_e32 vcc, v31, v29
	v_mov_b32_e32 v94, 0x358637bd
	s_mov_b32 s15, 0x800000
	v_cndmask_b32_e32 v31, v28, v31, vcc
	v_lshlrev_b32_e32 v91, 2, v31
	v_xor_b32_e32 v31, 2, v28
	v_cmp_lt_i32_e32 vcc, v31, v29
	s_nop 1
	v_cndmask_b32_e32 v31, v28, v31, vcc
	v_lshlrev_b32_e32 v92, 2, v31
	v_xor_b32_e32 v31, 1, v28
	v_cmp_lt_i32_e32 vcc, v31, v29
	v_mov_b32_e32 v29, v27
	s_nop 0
	v_cndmask_b32_e32 v28, v28, v31, vcc
	v_lshlrev_b32_e32 v93, 2, v28
	v_or_b32_e32 v28, 0x1000, v26
	v_lshl_add_u64 v[74:75], s[8:9], 0, v[28:29]
	v_or_b32_e32 v28, 0x1400, v26
	v_lshl_add_u64 v[76:77], s[8:9], 0, v[28:29]
	v_or_b32_e32 v28, 0x1800, v26
	v_or_b32_e32 v26, 0x1c00, v26
	v_lshl_add_u64 v[80:81], s[8:9], 0, v[26:27]
	v_lshlrev_b32_e32 v26, 1, v30
	v_lshl_add_u64 v[26:27], s[6:7], 0, v[26:27]
	s_mov_b64 s[6:7], 0x13300000
	v_lshl_add_u64 v[78:79], s[8:9], 0, v[28:29]
	v_lshl_add_u64 v[84:85], v[26:27], 0, s[6:7]
	s_mov_b64 s[8:9], 0
	s_branch .LBB0_174

; #define WAIT_V(n) asm volatile("s_waitcnt vmcnt(%0)" ::"n"(n) : "memory")
; #define BAR8 __builtin_amdgcn_s_barrier()
; __device__ __forceinline__ void gemm_main8(const u16* __restrict__ Ab, int lda, const u16* __restrict__ Bb, int ldb, int K,
;                                            char* shm, f32x4 (&acc)[2][2][4][2]) {
;     ...
;   __syncthreads();
;   WAIT_V(0);
;   STG_B(0, 0, 0); STG_A(0, 0, 0); STG_B(0, 1, 0); STG_A(0, 1, 0);
;   if (wr == 1) BAR8;
; __device__ __forceinline__ void run_gemm8(const GemmJob& J, char* shm) {
;     ...
;   for (int t = blockIdx.x; t < total; t += gridDim.x) {
;     const int z = t / per, u = t - z * per;
;     const int nig = WG * J.tN, gid0 = u / nig, v = u - gid0 * nig;
;     const int gid = J.rev ? (J.tM / WG - 1 - gid0) : gid0;
;     const int pm = gid * WG + v % WG, pn = v / WG;
;     const int brow = pm * 256, bcol = pn * 256;
;     f32x4 acc[2][2][4][2];
;     gemm_main8(J.A + z * J.sA + (long)brow * J.lda, J.lda, J.B + z * J.sB + (long)bcol * J.ldb, J.ldb, J.K, shm, acc);
.LBB0_659:
	s_and_b32 s13, s93, 0x73
	s_bfe_u32 s10, s93, 0x10002
	s_lshl_b32 s10, s10, 7
	s_or_b32 s13, s13, s10
	s_bfe_u32 s10, s93, 0x10007
	s_lshl_b32 s10, s10, 3
	s_or_b32 s13, s13, s10
	s_bfe_u32 s10, s93, 0x10003
	s_lshl_b32 s10, s10, 2
	s_or_b32 s13, s13, s10
	s_ashr_i32 s10, s13, 31
	s_lshr_b32 s10, s10, 25
	s_add_i32 s10, s13, s10
	s_ashr_i32 s12, s10, 7
	s_and_b32 s10, s10, 0xffffff80
	s_sub_i32 s10, s13, s10
	s_ashr_i32 s11, s10, 31
	s_lshr_b32 s11, s11, 25
	s_add_i32 s11, s10, s11
	s_and_b32 s13, s11, 0xffffff80
	s_sub_i32 s10, s10, s13
	s_ashr_i32 s13, s10, 31
	s_lshr_b32 s13, s13, 28
	s_add_i32 s13, s10, s13
	s_and_b32 s14, s13, 0xfffff0
	s_sub_i32 s10, s10, s14
	s_lshl_b32 s11, s11, 5
	s_and_b32 s11, s11, 0xfffff000
	s_lshl_b32 s10, s10, 8
	s_add_i32 s14, s10, s11
	s_lshl_b32 s10, s13, 4
	s_ashr_i32 s13, s12, 31
	s_and_b32 s18, s10, 0xffffff00
	s_lshl_b64 s[20:21], s[12:13], 26
	s_add_u32 s10, s36, s20
	s_addc_u32 s11, s72, s21
	s_ashr_i32 s15, s14, 31
	s_lshl_b64 s[24:25], s[14:15], 14
	v_mov_b32_e32 v139, v150
	s_add_u32 s10, s10, s24
	s_addc_u32 s11, s11, s25
	v_ashrrev_i32_e32 v6, 6, v139
	v_lshrrev_b32_e32 v0, 31, v139
	s_lshl_b64 s[88:89], s[12:13], 14
	v_add_u32_e32 v0, v6, v0
	s_add_u32 s15, s73, s88
	v_ashrrev_i32_e32 v5, 1, v0
	v_and_b32_e32 v0, 0x3fffffe, v0
	s_addc_u32 s78, s74, s89
	s_ashr_i32 s19, s18, 31
	v_lshlrev_b32_e32 v7, 4, v139
	v_sub_u32_e32 v0, v6, v0
	s_lshl_b64 s[90:91], s[18:19], 15
	v_and_b32_e32 v8, 32, v139
	v_bfe_u32 v4, v139, 2, 4
	v_lshlrev_b32_e32 v0, 6, v0
	v_and_b32_e32 v2, 48, v7
	v_lshlrev_b32_e32 v141, 10, v6
	s_add_u32 vcc_lo, s15, s90
	v_lshl_or_b32 v12, v5, 4, v4
	v_bitop3_b32 v0, v2, v0, v8 bitop3:0xde
	v_add_u32_e32 v142, 0x10000, v141
	s_addc_u32 vcc_hi, s78, s91
	v_lshl_add_u32 v0, v12, 15, v0
	v_readfirstlane_b32 s15, v142
	v_add_u32_e32 v143, 0x12000, v141
	s_barrier
	s_waitcnt vmcnt(0)
	v_lshl_add_u64 v[2:3], vcc, 0, v[0:1]
	s_mov_b32 m0, s15
	s_mov_b64 s[78:79], 0x200000
	v_readfirstlane_b32 s15, v143
	global_load_lds_dwordx4 v0, vcc
	v_lshl_add_u64 v[10:11], v[2:3], 0, s[78:79]
	s_mov_b32 m0, s15
	v_readfirstlane_b32 s15, v141
	global_load_lds_dwordx4 v[10:11], off
	v_lshlrev_b32_e32 v10, 14, v12
	v_sub_u32_e32 v0, v0, v10
	s_mov_b32 m0, s15
	v_add_u32_e32 v144, 0x2000, v141
	v_lshl_add_u64 v[130:131], s[10:11], 0, v[0:1]
	global_load_lds_dwordx4 v0, s[10:11]
	v_readfirstlane_b32 s10, v144
	v_lshl_add_u64 v[10:11], v[130:131], 0, s[80:81]
	s_mov_b32 m0, s10
	v_add_u32_e32 v145, 0x14000, v141
	s_mov_b64 s[10:11], 0x400000
	global_load_lds_dwordx4 v[10:11], off
	v_lshl_add_u64 v[10:11], v[2:3], 0, s[10:11]
	v_readfirstlane_b32 s10, v145
	s_mov_b32 m0, s10
	s_mov_b64 s[10:11], 0x600000
	v_add_u32_e32 v146, 0x16000, v141
	global_load_lds_dwordx4 v[10:11], off
	v_lshl_add_u64 v[10:11], v[2:3], 0, s[10:11]
	v_readfirstlane_b32 s10, v146
	v_add_u32_e32 v147, 0x4000, v141
	s_mov_b32 m0, s10
	v_readfirstlane_b32 s10, v147
	global_load_lds_dwordx4 v[10:11], off
	v_lshl_add_u64 v[10:11], v[130:131], 0, s[78:79]
	s_mov_b32 m0, s10
	s_mov_b64 s[10:11], 0x300000
	v_add_u32_e32 v148, 0x6000, v141
	global_load_lds_dwordx4 v[10:11], off
	v_lshl_add_u64 v[10:11], v[130:131], 0, s[10:11]
	v_readfirstlane_b32 s10, v148
	s_mov_b32 m0, s10
	v_ashrrev_i32_e32 v9, 8, v139
	global_load_lds_dwordx4 v[10:11], off
	v_cmp_eq_u32_e32 vcc, 1, v9
	s_and_saveexec_b64 s[10:11], vcc
	s_cbranch_execz .LBB0_661
	s_barrier

; __device__ __forceinline__ float sigmoidf_(float x) { return __builtin_amdgcn_rcpf(1.f + __builtin_amdgcn_exp2f(x * -1.4426950408889634f)); }
; #define WAIT_V(n) asm volatile("s_waitcnt vmcnt(%0)" ::"n"(n) : "memory")
; #define ROWS8 _Pragma("unroll") for (int ai = 0; ai < 2; ++ai) _Pragma("unroll") for (int m = 0; m < 4; ++m)
; __device__ __forceinline__ void gemm_main8(const u16* __restrict__ Ab, int lda, const u16* __restrict__ Bb, int ldb, int K,
;                                            char* shm, f32x4 (&acc)[2][2][4][2]) {
;     ...
;   bf16x8 At[4][2], B0[2][2], B1[2][2];
;   const int nt = K >> 6;
;   __syncthreads();
;   WAIT_V(0);
;   STG_B(0, 0, 0); STG_A(0, 0, 0); STG_B(0, 1, 0); STG_A(0, 1, 0);
; __device__ __forceinline__ void run_gemm8(const GemmJob& J, char* shm) {
;     ...
;       case EPI_GU: {
;         const int odd = fq & 1;
;         const int ocw = (bcol >> 1) + wc * 16 + (fq & 2) * 4 + odd * 64;
;         ROWS8 { const int row = r0 + ai * 128 + m * 16;
;           u32x2 w2[2];
; #pragma unroll
;           for (int bj = 0; bj < 2; ++bj) {
;             f32x4 g = acc[ai][bj][m][0], up = acc[ai][bj][m][1];
;             float h0 = g[0] * sigmoidf_(g[0]) * up[0], h1 = g[1] * sigmoidf_(g[1]) * up[1];
;             float h2 = g[2] * sigmoidf_(g[2]) * up[2], h3 = g[3] * sigmoidf_(g[3]) * up[3];
;             w2[bj] = u32x2{cvtpk(h0, h1), cvtpk(h2, h3)}; }
;           const u32x2 snd = odd ? w2[0] : w2[1];
;           u32x2 rcv; rcv[0] = __shfl_xor(snd[0], 16, 64); rcv[1] = __shfl_xor(snd[1], 16, 64);
;           const u32x4 o4 = odd ? u32x4{rcv[0], rcv[1], w2[1][0], w2[1][1]} : u32x4{w2[0][0], w2[0][1], rcv[0], rcv[1]};
;           *(u32x4*)(J.o16 + (long)row * FH + ocw) = o4; }
;       } break;
.LBB0_901:
	s_or_b64 exec, exec, s[10:11]
	s_add_i32 s78, s75, s22
	s_cmpk_lt_i32 s78, 0xb00
	s_cbranch_scc0 .Lat_gu_nopf
	s_mul_hi_i32 s10, s78, 0x2e8ba2e9
	s_lshr_b32 s11, s10, 31
	s_ashr_i32 s10, s10, 9
	s_add_i32 s10, s10, s11
	s_mulk_i32 s10, 0xb00
	s_sub_i32 s10, s78, s10
	s_mul_i32 s11, s10, 0xba3
	s_lshr_b32 s12, s11, 31
	s_ashr_i32 s11, s11, 22
	s_add_i32 s11, s11, s12
	s_sext_i32_i16 s11, s11
	s_mul_i32 s12, s11, 0xfffffa80
	s_add_i32 s10, s12, s10
	s_bfe_u32 s12, s10, 0x5001a
	s_add_i32 s12, s10, s12
	s_and_b32 s13, s12, 0xffe0
	s_sub_i32 s10, s10, s13
	s_sext_i32_i16 s10, s10
	s_lshl_b32 s11, s11, 13
	s_lshl_b32 s10, s10, 8
	s_sext_i32_i16 s12, s12
	s_add_i32 s10, s10, s11
	s_ashr_i32 s12, s12, 5
	s_ashr_i32 s11, s10, 31
	s_lshl_b32 s12, s12, 8
	s_lshl_b64 s[10:11], s[10:11], 12
	s_ashr_i32 s13, s12, 31
	s_lshl_b64 s[12:13], s[12:13], 12
	s_add_u32 s10, s36, s10
	s_addc_u32 s11, s72, s11
	s_add_u32 s12, s73, s12
	s_addc_u32 s13, s74, s13
	v_ashrrev_i32_e32 v204, 6, v150
	v_lshlrev_b32_e32 v206, 10, v150
	v_ashrrev_i32_e32 v207, 1, v204
	v_and_b32_e32 v205, 0x3fffffe, v204
	v_and_b32_e32 v208, 0xf000, v206
	v_lshlrev_b32_e32 v212, 10, v204
	v_lshlrev_b32_e32 v209, 4, v150
	v_sub_u32_e32 v205, v204, v205
	v_lshl_or_b32 v206, v207, 16, v208
	v_and_b32_e32 v210, 32, v150
	v_and_b32_e32 v211, 48, v209
	v_lshl_add_u32 v205, v205, 6, v206
	v_bitop3_b32 v205, v211, v205, v210 bitop3:0xde
	v_readfirstlane_b32 s78, v212
	v_add_u32_e32 v213, 0x40000, v205
	v_add_u32_e32 v214, 0x80000, v205
	v_add_u32_e32 v215, 0xc0000, v205
	s_add_i32 m0, s78, 0x10000
	s_nop 0
	global_load_lds_dwordx4 v205, s[12:13]
	s_add_i32 m0, s78, 0x12000
	s_nop 0
	global_load_lds_dwordx4 v213, s[12:13]
	s_mov_b32 m0, s78
	s_nop 0
	global_load_lds_dwordx4 v205, s[10:11]
	s_add_i32 m0, s78, 0x2000
	s_nop 0
	global_load_lds_dwordx4 v213, s[10:11]
	s_add_i32 m0, s78, 0x14000
	s_nop 0
	global_load_lds_dwordx4 v214, s[12:13]
	s_add_i32 m0, s78, 0x16000
	s_nop 0
	global_load_lds_dwordx4 v215, s[12:13]
	s_add_i32 m0, s78, 0x4000
	s_nop 0
	global_load_lds_dwordx4 v214, s[10:11]
	s_add_i32 m0, s78, 0x6000
	s_nop 0
	global_load_lds_dwordx4 v215, s[10:11]
.Lat_gu_nopf:
	v_mul_f32_e32 v0, 0xbfb8aa3b, v122
	v_exp_f32_e32 v130, v0
	v_add_u32_e32 v0, s20, v133
	v_or_b32_e32 v131, s24, v134
	v_mov_b32_e32 v136, v132
	v_add_f32_e32 v130, 1.0, v130
	v_rcp_f32_e32 v130, v130
	v_mul_f32_e32 v137, 0xbfb8aa3b, v123
	s_add_i32 s75, s75, s22
	v_exp_f32_e32 v131, v137
	v_mul_f32_e32 v122, v122, v130
	v_mul_f32_e32 v122, v126, v122
	v_mul_f32_e32 v130, 0xbfb8aa3b, v124
	v_add_f32_e32 v126, 1.0, v131
	v_rcp_f32_e32 v126, v126
	v_mul_f32_e32 v131, 0xbfb8aa3b, v125
	v_exp_f32_e32 v131, v131
	v_exp_f32_e32 v130, v130
	v_mul_f32_e32 v123, v123, v126
	v_mul_f32_e32 v123, v127, v123
	v_mul_f32_e32 v127, 0xbfb8aa3b, v114
	v_add_f32_e32 v126, 1.0, v131
	v_exp_f32_e32 v127, v127
	v_rcp_f32_e32 v126, v126
	v_add_f32_e32 v130, 1.0, v130
	v_rcp_f32_e32 v130, v130
	v_cvt_pk_bf16_f32 v123, v122, v123
	v_add_f32_e32 v122, 1.0, v127
	v_mul_f32_e32 v125, v125, v126
	v_rcp_f32_e32 v122, v122
	v_mul_f32_e32 v126, 0xbfb8aa3b, v115
	v_exp_f32_e32 v126, v126
	v_mul_f32_e32 v124, v124, v130
	v_mul_f32_e32 v124, v128, v124
	v_mul_f32_e32 v125, v129, v125
	v_mul_f32_e32 v114, v114, v122
	v_cvt_pk_bf16_f32 v124, v124, v125
	v_mul_f32_e32 v114, v118, v114
	v_add_f32_e32 v118, 1.0, v126
	v_mul_f32_e32 v122, 0xbfb8aa3b, v116
	v_mul_f32_e32 v125, 0xbfb8aa3b, v117
	v_rcp_f32_e32 v118, v118
	v_exp_f32_e32 v122, v122
	v_exp_f32_e32 v125, v125
	s_cmpk_lt_i32 s75, 0xb00
	v_mul_f32_e32 v115, v115, v118
	v_add_f32_e32 v118, 1.0, v122
	v_add_f32_e32 v122, 1.0, v125
	v_rcp_f32_e32 v122, v122
	v_rcp_f32_e32 v118, v118
	v_mul_f32_e32 v115, v119, v115
	v_cvt_pk_bf16_f32 v114, v114, v115
	v_mul_f32_e32 v117, v117, v122
	v_mul_f32_e32 v116, v116, v118
	v_mul_f32_e32 v117, v121, v117
	v_and_b32_e32 v118, 64, v151
	v_mul_f32_e32 v116, v120, v116
	v_cvt_pk_bf16_f32 v115, v116, v117
	v_xor_b32_e32 v117, 16, v151
	v_add_u32_e32 v118, 64, v118
	v_cmp_lt_i32_e64 s[12:13], v117, v118
	v_cndmask_b32_e32 v116, v123, v114, vcc
	s_nop 0
	v_cndmask_b32_e64 v117, v151, v117, s[12:13]
	v_lshlrev_b32_e32 v118, 2, v117
	ds_bpermute_b32 v119, v118, v116
	v_cndmask_b32_e32 v116, v124, v115, vcc
	ds_bpermute_b32 v121, v118, v116
	v_lshl_or_b32 v116, s90, 7, v135
	v_ashrrev_i32_e32 v117, 31, v116
	s_waitcnt lgkmcnt(0)
	v_cndmask_b32_e32 v122, v114, v119, vcc
	v_mul_f32_e32 v114, 0xbfb8aa3b, v106
	v_cndmask_b32_e32 v120, v119, v123, vcc
	v_exp_f32_e32 v119, v114
	v_cndmask_b32_e32 v123, v115, v121, vcc
	v_mov_b64_e32 v[114:115], s[18:19]
	v_cndmask_b32_e32 v121, v121, v124, vcc
	v_add_f32_e32 v119, 1.0, v119
	v_rcp_f32_e32 v119, v119
	v_mad_i64_i32 v[124:125], s[10:11], v0, s35, v[114:115]
	v_lshlrev_b64 v[116:117], 1, v[116:117]
	v_mul_f32_e32 v106, v106, v119
	v_mul_f32_e32 v119, 0xbfb8aa3b, v107
	v_lshl_add_u64 v[124:125], v[124:125], 0, v[116:117]
	v_exp_f32_e32 v119, v119
	global_store_dwordx4 v[124:125], v[120:123], off
	v_mul_f32_e32 v106, v110, v106
	v_add_f32_e32 v110, 1.0, v119
	v_mul_f32_e32 v120, 0xbfb8aa3b, v108
	v_exp_f32_e32 v120, v120
	v_rcp_f32_e32 v110, v110
	v_add_f32_e32 v119, 1.0, v120
	v_mul_f32_e32 v120, 0xbfb8aa3b, v109
	v_exp_f32_e32 v120, v120
	v_mul_f32_e32 v107, v107, v110
	v_mul_f32_e32 v107, v111, v107
	v_mul_f32_e32 v111, 0xbfb8aa3b, v98
	v_add_f32_e32 v110, 1.0, v120
	v_exp_f32_e32 v111, v111
	v_rcp_f32_e32 v110, v110
	v_rcp_f32_e32 v119, v119
	v_cvt_pk_bf16_f32 v106, v106, v107
	v_add_f32_e32 v107, 1.0, v111
	v_mul_f32_e32 v109, v109, v110
	v_rcp_f32_e32 v107, v107
	v_mul_f32_e32 v110, 0xbfb8aa3b, v99
	v_exp_f32_e32 v110, v110
	v_mul_f32_e32 v108, v108, v119
	v_mul_f32_e32 v108, v112, v108
	v_mul_f32_e32 v109, v113, v109
	v_mul_f32_e32 v98, v98, v107
	v_cvt_pk_bf16_f32 v108, v108, v109
	v_mul_f32_e32 v98, v102, v98
	v_add_f32_e32 v102, 1.0, v110
	v_mul_f32_e32 v107, 0xbfb8aa3b, v100
	v_mul_f32_e32 v109, 0xbfb8aa3b, v101
	v_rcp_f32_e32 v102, v102
	v_exp_f32_e32 v107, v107
	v_exp_f32_e32 v109, v109
	v_mul_f32_e32 v99, v99, v102
	v_add_f32_e32 v102, 1.0, v107
	v_add_f32_e32 v107, 1.0, v109
	v_rcp_f32_e32 v102, v102
	v_rcp_f32_e32 v107, v107
	v_mul_f32_e32 v99, v103, v99
	v_cvt_pk_bf16_f32 v98, v98, v99
	v_mul_f32_e32 v100, v100, v102
	v_cndmask_b32_e32 v99, v106, v98, vcc
	ds_bpermute_b32 v99, v118, v99
	v_mul_f32_e32 v101, v101, v107
	v_mul_f32_e32 v100, v104, v100
	v_mul_f32_e32 v101, v105, v101
	v_cvt_pk_bf16_f32 v101, v100, v101
	v_add_u32_e32 v102, 16, v0
	v_cndmask_b32_e32 v100, v108, v101, vcc
	ds_bpermute_b32 v103, v118, v100
	s_waitcnt lgkmcnt(0)
; __device__ __forceinline__ float sigmoidf_(float x) { return __builtin_amdgcn_rcpf(1.f + __builtin_amdgcn_exp2f(x * -1.4426950408889634f)); }
; #define ROWS8 _Pragma("unroll") for (int ai = 0; ai < 2; ++ai) _Pragma("unroll") for (int m = 0; m < 4; ++m)
; __device__ __forceinline__ void run_gemm8(const GemmJob& J, char* shm) {
;     ...
;         ROWS8 { const int row = r0 + ai * 128 + m * 16;
;           u32x2 w2[2];
; #pragma unroll
;           for (int bj = 0; bj < 2; ++bj) {
;             f32x4 g = acc[ai][bj][m][0], up = acc[ai][bj][m][1];
;             float h0 = g[0] * sigmoidf_(g[0]) * up[0], h1 = g[1] * sigmoidf_(g[1]) * up[1];
;             float h2 = g[2] * sigmoidf_(g[2]) * up[2], h3 = g[3] * sigmoidf_(g[3]) * up[3];
;             w2[bj] = u32x2{cvtpk(h0, h1), cvtpk(h2, h3)}; }
;           const u32x2 snd = odd ? w2[0] : w2[1];
;           u32x2 rcv; rcv[0] = __shfl_xor(snd[0], 16, 64); rcv[1] = __shfl_xor(snd[1], 16, 64);
;           const u32x4 o4 = odd ? u32x4{rcv[0], rcv[1], w2[1][0], w2[1][1]} : u32x4{w2[0][0], w2[0][1], rcv[0], rcv[1]};
;           *(u32x4*)(J.o16 + (long)row * FH + ocw) = o4; }
	v_cndmask_b32_e32 v100, v98, v99, vcc
	v_mul_f32_e32 v98, 0xbfb8aa3b, v90
	v_exp_f32_e32 v104, v98
	v_cndmask_b32_e32 v98, v99, v106, vcc
	v_cndmask_b32_e32 v101, v101, v103, vcc
	v_cndmask_b32_e32 v99, v103, v108, vcc
	v_add_f32_e32 v103, 1.0, v104
	v_rcp_f32_e32 v104, v103
	v_mad_i64_i32 v[102:103], s[10:11], v102, s35, v[114:115]
	v_lshl_add_u64 v[102:103], v[102:103], 0, v[116:117]
	global_store_dwordx4 v[102:103], v[98:101], off
	v_mul_f32_e32 v90, v90, v104
	v_mul_f32_e32 v90, v94, v90
	v_mul_f32_e32 v98, 0xbfb8aa3b, v91
	v_exp_f32_e32 v98, v98
	v_mul_f32_e32 v99, 0xbfb8aa3b, v92
	v_exp_f32_e32 v99, v99
	v_add_f32_e32 v94, 1.0, v98
	v_rcp_f32_e32 v94, v94
	v_add_f32_e32 v98, 1.0, v99
	v_mul_f32_e32 v99, 0xbfb8aa3b, v93
	v_exp_f32_e32 v99, v99
	v_mul_f32_e32 v91, v91, v94
	v_mul_f32_e32 v91, v95, v91
	v_mul_f32_e32 v95, 0xbfb8aa3b, v82
	v_add_f32_e32 v94, 1.0, v99
	v_exp_f32_e32 v95, v95
	v_rcp_f32_e32 v94, v94
	v_rcp_f32_e32 v98, v98
	v_cvt_pk_bf16_f32 v90, v90, v91
	v_add_f32_e32 v91, 1.0, v95
	v_mul_f32_e32 v93, v93, v94
	v_rcp_f32_e32 v91, v91
	v_mul_f32_e32 v94, 0xbfb8aa3b, v83
	v_exp_f32_e32 v94, v94
	v_mul_f32_e32 v92, v92, v98
	v_mul_f32_e32 v92, v96, v92
	v_mul_f32_e32 v93, v97, v93
	v_mul_f32_e32 v82, v82, v91
	v_cvt_pk_bf16_f32 v92, v92, v93
	v_mul_f32_e32 v82, v86, v82
	v_add_f32_e32 v86, 1.0, v94
	v_mul_f32_e32 v91, 0xbfb8aa3b, v84
	v_mul_f32_e32 v93, 0xbfb8aa3b, v85
	v_rcp_f32_e32 v86, v86
	v_exp_f32_e32 v91, v91
	v_exp_f32_e32 v93, v93
	v_mul_f32_e32 v83, v83, v86
	v_add_f32_e32 v86, 1.0, v91
	v_add_f32_e32 v91, 1.0, v93
	v_rcp_f32_e32 v86, v86
	v_rcp_f32_e32 v91, v91
	v_mul_f32_e32 v83, v87, v83
	v_cvt_pk_bf16_f32 v82, v82, v83
	v_mul_f32_e32 v84, v84, v86
	v_cndmask_b32_e32 v83, v90, v82, vcc
	ds_bpermute_b32 v83, v118, v83
	v_mul_f32_e32 v85, v85, v91
	v_mul_f32_e32 v84, v88, v84
	v_mul_f32_e32 v85, v89, v85
	v_cvt_pk_bf16_f32 v85, v84, v85
	v_add_u32_e32 v86, 32, v0
	v_cndmask_b32_e32 v84, v92, v85, vcc
	ds_bpermute_b32 v87, v118, v84
	s_waitcnt lgkmcnt(0)
	v_cndmask_b32_e32 v84, v82, v83, vcc
	v_mul_f32_e32 v82, 0xbfb8aa3b, v74
	v_exp_f32_e32 v88, v82
	v_cndmask_b32_e32 v82, v83, v90, vcc
	v_cndmask_b32_e32 v85, v85, v87, vcc
	v_cndmask_b32_e32 v83, v87, v92, vcc
	v_add_f32_e32 v87, 1.0, v88
	v_rcp_f32_e32 v88, v87
	v_mad_i64_i32 v[86:87], s[10:11], v86, s35, v[114:115]
	v_lshl_add_u64 v[86:87], v[86:87], 0, v[116:117]
	global_store_dwordx4 v[86:87], v[82:85], off
	v_mul_f32_e32 v74, v74, v88
	v_mul_f32_e32 v74, v78, v74
	v_mul_f32_e32 v82, 0xbfb8aa3b, v75
	v_exp_f32_e32 v82, v82
	v_mul_f32_e32 v83, 0xbfb8aa3b, v76
	v_exp_f32_e32 v83, v83
	v_add_f32_e32 v78, 1.0, v82
	v_rcp_f32_e32 v78, v78
	v_add_f32_e32 v82, 1.0, v83
	v_mul_f32_e32 v83, 0xbfb8aa3b, v77
	v_exp_f32_e32 v83, v83
	v_mul_f32_e32 v75, v75, v78
	v_mul_f32_e32 v75, v79, v75
	v_mul_f32_e32 v79, 0xbfb8aa3b, v66
	v_add_f32_e32 v78, 1.0, v83
	v_exp_f32_e32 v79, v79
	v_rcp_f32_e32 v78, v78
	v_cvt_pk_bf16_f32 v74, v74, v75
	v_rcp_f32_e32 v82, v82
	v_add_f32_e32 v75, 1.0, v79
	v_mul_f32_e32 v77, v77, v78
	v_rcp_f32_e32 v75, v75
	v_mul_f32_e32 v78, 0xbfb8aa3b, v67
	v_exp_f32_e32 v78, v78
	v_mul_f32_e32 v76, v76, v82
	v_mul_f32_e32 v66, v66, v75
	v_mul_f32_e32 v76, v80, v76
	v_mul_f32_e32 v77, v81, v77
	v_mul_f32_e32 v66, v70, v66
	v_add_f32_e32 v70, 1.0, v78
	v_mul_f32_e32 v75, 0xbfb8aa3b, v68
	v_cvt_pk_bf16_f32 v76, v76, v77
	v_rcp_f32_e32 v70, v70
	v_exp_f32_e32 v75, v75
	v_mul_f32_e32 v77, 0xbfb8aa3b, v69
	v_exp_f32_e32 v77, v77
	v_mul_f32_e32 v67, v67, v70
	v_add_f32_e32 v70, 1.0, v75
	v_rcp_f32_e32 v70, v70
	v_add_f32_e32 v75, 1.0, v77
	v_rcp_f32_e32 v75, v75
	v_mul_f32_e32 v67, v71, v67
	v_mul_f32_e32 v68, v68, v70
	v_mul_f32_e32 v68, v72, v68
	v_mul_f32_e32 v69, v69, v75
	v_mul_f32_e32 v69, v73, v69
	v_cvt_pk_bf16_f32 v66, v66, v67
	v_cvt_pk_bf16_f32 v67, v68, v69
	v_add_u32_e32 v71, 48, v0
	v_cndmask_b32_e32 v68, v74, v66, vcc
	ds_bpermute_b32 v69, v118, v68
	v_cndmask_b32_e32 v68, v76, v67, vcc
	ds_bpermute_b32 v70, v118, v68
	s_waitcnt lgkmcnt(0)
	v_cndmask_b32_e32 v68, v66, v69, vcc
	v_cndmask_b32_e32 v66, v69, v74, vcc
	v_cndmask_b32_e32 v69, v67, v70, vcc
	v_mul_f32_e32 v67, 0xbfb8aa3b, v58
	v_exp_f32_e32 v72, v67
	v_cndmask_b32_e32 v67, v70, v76, vcc
	v_mad_i64_i32 v[70:71], s[10:11], v71, s35, v[114:115]
	v_add_f32_e32 v72, 1.0, v72
	v_lshl_add_u64 v[70:71], v[70:71], 0, v[116:117]
	v_rcp_f32_e32 v72, v72
	global_store_dwordx4 v[70:71], v[66:69], off
	v_mul_f32_e32 v58, v58, v72
	s_nop 0
	v_mul_f32_e32 v67, 0xbfb8aa3b, v59
	v_exp_f32_e32 v67, v67
	v_mul_f32_e32 v68, 0xbfb8aa3b, v60
	v_exp_f32_e32 v68, v68
	v_mul_f32_e32 v58, v62, v58
	v_add_f32_e32 v62, 1.0, v67
	v_rcp_f32_e32 v62, v62
	v_add_f32_e32 v67, 1.0, v68
	v_mul_f32_e32 v68, 0xbfb8aa3b, v61
	v_exp_f32_e32 v68, v68
	v_mul_f32_e32 v59, v59, v62
	v_mul_f32_e32 v59, v63, v59
	v_mul_f32_e32 v63, 0xbfb8aa3b, v54
	v_add_f32_e32 v62, 1.0, v68
	v_exp_f32_e32 v63, v63
	v_rcp_f32_e32 v62, v62
	v_cvt_pk_bf16_f32 v58, v58, v59
	v_rcp_f32_e32 v67, v67
	v_add_f32_e32 v59, 1.0, v63
	v_mul_f32_e32 v61, v61, v62
	v_rcp_f32_e32 v59, v59
	v_mul_f32_e32 v62, 0xbfb8aa3b, v55
	v_exp_f32_e32 v62, v62
	v_mul_f32_e32 v60, v60, v67
	v_mul_f32_e32 v54, v54, v59
	v_mul_f32_e32 v60, v64, v60
	v_mul_f32_e32 v61, v65, v61
	v_mul_f32_e32 v50, v50, v54
	v_add_f32_e32 v54, 1.0, v62
	v_mul_f32_e32 v59, 0xbfb8aa3b, v56
	v_cvt_pk_bf16_f32 v60, v60, v61
	v_rcp_f32_e32 v54, v54
	v_exp_f32_e32 v59, v59
	v_mul_f32_e32 v61, 0xbfb8aa3b, v57
	v_exp_f32_e32 v61, v61
	v_mul_f32_e32 v54, v55, v54
	v_add_f32_e32 v55, 1.0, v59
	v_rcp_f32_e32 v55, v55
	v_add_f32_e32 v59, 1.0, v61
	v_rcp_f32_e32 v59, v59
	v_mul_f32_e32 v51, v51, v54
	v_cvt_pk_bf16_f32 v50, v50, v51
	v_mul_f32_e32 v54, v56, v55
	v_cndmask_b32_e32 v51, v58, v50, vcc
	ds_bpermute_b32 v51, v118, v51
	v_mul_f32_e32 v52, v52, v54
	v_mul_f32_e32 v54, v57, v59
	v_mul_f32_e32 v53, v53, v54
	v_cvt_pk_bf16_f32 v53, v52, v53
	v_add_u32_e32 v66, 0x80, v0
	v_cndmask_b32_e32 v52, v60, v53, vcc
	ds_bpermute_b32 v54, v118, v52
	s_waitcnt lgkmcnt(0)
; __device__ __forceinline__ float sigmoidf_(float x) { return __builtin_amdgcn_rcpf(1.f + __builtin_amdgcn_exp2f(x * -1.4426950408889634f)); }
; #define ROWS8 _Pragma("unroll") for (int ai = 0; ai < 2; ++ai) _Pragma("unroll") for (int m = 0; m < 4; ++m)
; __device__ __forceinline__ void run_gemm8(const GemmJob& J, char* shm) {
;     ...
;   for (int t = blockIdx.x; t < total; t += gridDim.x) {
;     ...
;         ROWS8 { const int row = r0 + ai * 128 + m * 16;
;           u32x2 w2[2];
; #pragma unroll
;           for (int bj = 0; bj < 2; ++bj) {
;             f32x4 g = acc[ai][bj][m][0], up = acc[ai][bj][m][1];
;             float h0 = g[0] * sigmoidf_(g[0]) * up[0], h1 = g[1] * sigmoidf_(g[1]) * up[1];
;             float h2 = g[2] * sigmoidf_(g[2]) * up[2], h3 = g[3] * sigmoidf_(g[3]) * up[3];
;             w2[bj] = u32x2{cvtpk(h0, h1), cvtpk(h2, h3)}; }
;           const u32x2 snd = odd ? w2[0] : w2[1];
;           u32x2 rcv; rcv[0] = __shfl_xor(snd[0], 16, 64); rcv[1] = __shfl_xor(snd[1], 16, 64);
;           const u32x4 o4 = odd ? u32x4{rcv[0], rcv[1], w2[1][0], w2[1][1]} : u32x4{w2[0][0], w2[0][1], rcv[0], rcv[1]};
;           *(u32x4*)(J.o16 + (long)row * FH + ocw) = o4; }
	v_cndmask_b32_e32 v52, v50, v51, vcc
	v_mul_f32_e32 v50, 0xbfb8aa3b, v42
	v_exp_f32_e32 v55, v50
	v_cndmask_b32_e32 v50, v51, v58, vcc
	v_cndmask_b32_e32 v53, v53, v54, vcc
	v_cndmask_b32_e32 v51, v54, v60, vcc
	v_add_f32_e32 v54, 1.0, v55
	v_rcp_f32_e32 v56, v54
	v_mad_i64_i32 v[54:55], s[10:11], v66, s35, v[114:115]
	v_lshl_add_u64 v[54:55], v[54:55], 0, v[116:117]
	global_store_dwordx4 v[54:55], v[50:53], off
	v_mul_f32_e32 v42, v42, v56
	v_mul_f32_e32 v42, v46, v42
	v_mul_f32_e32 v50, 0xbfb8aa3b, v43
	v_exp_f32_e32 v50, v50
	v_mul_f32_e32 v51, 0xbfb8aa3b, v44
	v_exp_f32_e32 v51, v51
	v_add_f32_e32 v46, 1.0, v50
	v_rcp_f32_e32 v46, v46
	v_add_f32_e32 v50, 1.0, v51
	v_mul_f32_e32 v51, 0xbfb8aa3b, v45
	v_exp_f32_e32 v51, v51
	v_mul_f32_e32 v43, v43, v46
	v_mul_f32_e32 v43, v47, v43
	v_mul_f32_e32 v47, 0xbfb8aa3b, v34
	v_add_f32_e32 v46, 1.0, v51
	v_exp_f32_e32 v47, v47
	v_rcp_f32_e32 v46, v46
	v_rcp_f32_e32 v50, v50
	v_cvt_pk_bf16_f32 v42, v42, v43
	v_add_f32_e32 v43, 1.0, v47
	v_mul_f32_e32 v45, v45, v46
	v_rcp_f32_e32 v43, v43
	v_mul_f32_e32 v46, 0xbfb8aa3b, v35
	v_exp_f32_e32 v46, v46
	v_mul_f32_e32 v44, v44, v50
	v_mul_f32_e32 v44, v48, v44
	v_mul_f32_e32 v45, v49, v45
	v_mul_f32_e32 v34, v34, v43
	v_cvt_pk_bf16_f32 v44, v44, v45
	v_mul_f32_e32 v34, v38, v34
	v_add_f32_e32 v38, 1.0, v46
	v_mul_f32_e32 v43, 0xbfb8aa3b, v36
	v_mul_f32_e32 v45, 0xbfb8aa3b, v37
	v_rcp_f32_e32 v38, v38
	v_exp_f32_e32 v43, v43
	v_exp_f32_e32 v45, v45
	v_mul_f32_e32 v35, v35, v38
	v_add_f32_e32 v38, 1.0, v43
	v_add_f32_e32 v43, 1.0, v45
	v_rcp_f32_e32 v38, v38
	v_rcp_f32_e32 v43, v43
	v_mul_f32_e32 v35, v39, v35
	v_cvt_pk_bf16_f32 v34, v34, v35
	v_mul_f32_e32 v36, v36, v38
	v_cndmask_b32_e32 v35, v42, v34, vcc
	ds_bpermute_b32 v35, v118, v35
	v_mul_f32_e32 v37, v37, v43
	v_mul_f32_e32 v36, v40, v36
	v_mul_f32_e32 v37, v41, v37
	v_cvt_pk_bf16_f32 v37, v36, v37
	v_add_u32_e32 v38, 0x90, v0
	v_cndmask_b32_e32 v36, v44, v37, vcc
	ds_bpermute_b32 v39, v118, v36
	s_waitcnt lgkmcnt(0)
	v_cndmask_b32_e32 v36, v34, v35, vcc
	v_mul_f32_e32 v34, 0xbfb8aa3b, v26
	v_exp_f32_e32 v40, v34
	v_cndmask_b32_e32 v34, v35, v42, vcc
	v_cndmask_b32_e32 v37, v37, v39, vcc
	v_cndmask_b32_e32 v35, v39, v44, vcc
	v_add_f32_e32 v39, 1.0, v40
	v_rcp_f32_e32 v40, v39
	v_mad_i64_i32 v[38:39], s[10:11], v38, s35, v[114:115]
	v_lshl_add_u64 v[38:39], v[38:39], 0, v[116:117]
	global_store_dwordx4 v[38:39], v[34:37], off
	v_mul_f32_e32 v26, v26, v40
	v_mul_f32_e32 v26, v30, v26
	v_mul_f32_e32 v34, 0xbfb8aa3b, v27
	v_exp_f32_e32 v34, v34
	v_mul_f32_e32 v35, 0xbfb8aa3b, v28
	v_exp_f32_e32 v35, v35
	v_add_f32_e32 v30, 1.0, v34
	v_rcp_f32_e32 v30, v30
	v_add_f32_e32 v34, 1.0, v35
	v_mul_f32_e32 v35, 0xbfb8aa3b, v29
	v_exp_f32_e32 v35, v35
	v_mul_f32_e32 v27, v27, v30
	v_mul_f32_e32 v27, v31, v27
	v_mul_f32_e32 v31, 0xbfb8aa3b, v18
	v_add_f32_e32 v30, 1.0, v35
	v_exp_f32_e32 v31, v31
	v_rcp_f32_e32 v30, v30
	v_rcp_f32_e32 v34, v34
	v_cvt_pk_bf16_f32 v26, v26, v27
	v_add_f32_e32 v27, 1.0, v31
	v_mul_f32_e32 v29, v29, v30
	v_rcp_f32_e32 v27, v27
	v_mul_f32_e32 v30, 0xbfb8aa3b, v19
	v_exp_f32_e32 v30, v30
	v_mul_f32_e32 v28, v28, v34
	v_mul_f32_e32 v28, v32, v28
	v_mul_f32_e32 v29, v33, v29
	v_mul_f32_e32 v18, v18, v27
	v_cvt_pk_bf16_f32 v28, v28, v29
	v_mul_f32_e32 v18, v22, v18
	v_add_f32_e32 v22, 1.0, v30
	v_mul_f32_e32 v27, 0xbfb8aa3b, v20
	v_mul_f32_e32 v29, 0xbfb8aa3b, v21
	v_rcp_f32_e32 v22, v22
	v_exp_f32_e32 v27, v27
	v_exp_f32_e32 v29, v29
	v_mul_f32_e32 v19, v19, v22
	v_add_f32_e32 v22, 1.0, v27
	v_add_f32_e32 v27, 1.0, v29
	v_rcp_f32_e32 v22, v22
	v_rcp_f32_e32 v27, v27
	v_mul_f32_e32 v19, v23, v19
	v_cvt_pk_bf16_f32 v18, v18, v19
	v_mul_f32_e32 v20, v20, v22
	v_cndmask_b32_e32 v19, v26, v18, vcc
	ds_bpermute_b32 v19, v118, v19
	v_mul_f32_e32 v21, v21, v27
	v_mul_f32_e32 v20, v24, v20
	v_mul_f32_e32 v21, v25, v21
	v_cvt_pk_bf16_f32 v21, v20, v21
	v_add_u32_e32 v22, 0xa0, v0
	v_cndmask_b32_e32 v20, v28, v21, vcc
	ds_bpermute_b32 v23, v118, v20
	s_waitcnt lgkmcnt(0)
	v_cndmask_b32_e32 v20, v18, v19, vcc
	v_mul_f32_e32 v18, 0xbfb8aa3b, v10
	v_exp_f32_e32 v24, v18
	v_cndmask_b32_e32 v18, v19, v26, vcc
	v_cndmask_b32_e32 v21, v21, v23, vcc
	v_cndmask_b32_e32 v19, v23, v28, vcc
	v_add_f32_e32 v23, 1.0, v24
	v_rcp_f32_e32 v24, v23
	v_mad_i64_i32 v[22:23], s[10:11], v22, s35, v[114:115]
	v_lshl_add_u64 v[22:23], v[22:23], 0, v[116:117]
	global_store_dwordx4 v[22:23], v[18:21], off
	v_mul_f32_e32 v10, v10, v24
	v_mul_f32_e32 v10, v14, v10
	v_mul_f32_e32 v18, 0xbfb8aa3b, v11
	v_exp_f32_e32 v18, v18
	v_mul_f32_e32 v19, 0xbfb8aa3b, v12
	v_exp_f32_e32 v19, v19
	v_add_u32_e32 v0, 0xb0, v0
	v_add_f32_e32 v14, 1.0, v18
	v_rcp_f32_e32 v14, v14
	v_add_f32_e32 v18, 1.0, v19
	v_mul_f32_e32 v19, 0xbfb8aa3b, v13
	v_exp_f32_e32 v19, v19
	v_mul_f32_e32 v11, v11, v14
	v_mul_f32_e32 v11, v15, v11
	v_mul_f32_e32 v15, 0xbfb8aa3b, v2
	v_add_f32_e32 v14, 1.0, v19
	v_exp_f32_e32 v15, v15
	v_rcp_f32_e32 v14, v14
	v_cvt_pk_bf16_f32 v10, v10, v11
	v_rcp_f32_e32 v18, v18
	v_add_f32_e32 v11, 1.0, v15
	v_mul_f32_e32 v13, v13, v14
	v_rcp_f32_e32 v11, v11
	v_mul_f32_e32 v14, 0xbfb8aa3b, v3
	v_exp_f32_e32 v14, v14
	v_mul_f32_e32 v12, v12, v18
	v_mul_f32_e32 v2, v2, v11
	v_mul_f32_e32 v12, v16, v12
	v_mul_f32_e32 v13, v17, v13
	v_mul_f32_e32 v2, v6, v2
	v_add_f32_e32 v6, 1.0, v14
	v_mul_f32_e32 v11, 0xbfb8aa3b, v4
	v_cvt_pk_bf16_f32 v12, v12, v13
	v_rcp_f32_e32 v6, v6
	v_exp_f32_e32 v11, v11
	v_mul_f32_e32 v13, 0xbfb8aa3b, v5
	v_exp_f32_e32 v13, v13
	v_mul_f32_e32 v3, v3, v6
	v_add_f32_e32 v6, 1.0, v11
	v_rcp_f32_e32 v6, v6
	v_add_f32_e32 v11, 1.0, v13
	v_rcp_f32_e32 v11, v11
	v_mul_f32_e32 v3, v7, v3
	v_mul_f32_e32 v4, v4, v6
	v_mul_f32_e32 v4, v8, v4
	v_mul_f32_e32 v5, v5, v11
	v_mul_f32_e32 v5, v9, v5
	v_cvt_pk_bf16_f32 v2, v2, v3
	v_cvt_pk_bf16_f32 v3, v4, v5
	s_nop 0
	v_cndmask_b32_e32 v4, v10, v2, vcc
	ds_bpermute_b32 v5, v118, v4
	v_cndmask_b32_e32 v4, v12, v3, vcc
	ds_bpermute_b32 v6, v118, v4
	s_waitcnt lgkmcnt(0)
	v_cndmask_b32_e32 v4, v2, v5, vcc
	v_cndmask_b32_e32 v2, v5, v10, vcc
	v_cndmask_b32_e32 v5, v3, v6, vcc
	v_cndmask_b32_e32 v3, v6, v12, vcc
	v_mad_i64_i32 v[6:7], s[10:11], v0, s35, v[114:115]
	v_lshl_add_u64 v[6:7], v[6:7], 0, v[116:117]
	global_store_dwordx4 v[6:7], v[2:5], off
	s_cbranch_scc0 .LBB0_908
; #define WAIT_V(n) asm volatile("s_waitcnt vmcnt(%0)" ::"n"(n) : "memory")
; #define BAR8 __builtin_amdgcn_s_barrier()
; __device__ __forceinline__ void gemm_main8(const u16* __restrict__ Ab, int lda, const u16* __restrict__ Bb, int ldb, int K,
;                                            char* shm, f32x4 (&acc)[2][2][4][2]) {
;     ...
;   __syncthreads();
;   WAIT_V(0);
;   STG_B(0, 0, 0); STG_A(0, 0, 0); STG_B(0, 1, 0); STG_A(0, 1, 0);
;   if (wr == 1) BAR8;
;   WAIT_V(4); BAR8;
;   STG_B(1, 0, 1); STG_A(1, 0, 1); STG_B(1, 1, 1);
; __device__ __forceinline__ void run_gemm8(const GemmJob& J, char* shm) {
;     ...
;   for (int t = blockIdx.x; t < total; t += gridDim.x) {
;     const int z = t / per, u = t - z * per;
;     const int nig = WG * J.tN, gid0 = u / nig, v = u - gid0 * nig;
;     const int gid = J.rev ? (J.tM / WG - 1 - gid0) : gid0;
;     const int pm = gid * WG + v % WG, pn = v / WG;
;     const int brow = pm * 256, bcol = pn * 256;
;     f32x4 acc[2][2][4][2];
;     gemm_main8(J.A + z * J.sA + (long)brow * J.lda, J.lda, J.B + z * J.sB + (long)bcol * J.ldb, J.ldb, J.K, shm, acc);
.LBB0_902:
	s_mul_hi_i32 s10, s75, 0x2e8ba2e9
	s_lshr_b32 s11, s10, 31
	s_ashr_i32 s10, s10, 9
	s_add_i32 s10, s10, s11
	s_mulk_i32 s10, 0xb00
	s_sub_i32 s10, s75, s10
	s_mul_i32 s11, s10, 0xba3
	s_lshr_b32 s12, s11, 31
	s_ashr_i32 s11, s11, 22
	s_add_i32 s11, s11, s12
	s_sext_i32_i16 s11, s11
	s_mul_i32 s12, s11, 0xfffffa80
	s_add_i32 s10, s12, s10
	s_bfe_u32 s12, s10, 0x5001a
	s_add_i32 s12, s10, s12
	s_and_b32 s13, s12, 0xffe0
	s_sub_i32 s10, s10, s13
	s_sext_i32_i16 s10, s10
	s_lshl_b32 s11, s11, 13
	s_lshl_b32 s10, s10, 8
	s_sext_i32_i16 s12, s12
	s_add_i32 s20, s10, s11
	s_ashr_i32 s90, s12, 5
	s_ashr_i32 s21, s20, 31
	v_mov_b32_e32 v136, v150
	s_lshl_b32 s24, s90, 8
	s_lshl_b64 s[28:29], s[20:21], 12
	s_add_u32 s10, s36, s28
	v_ashrrev_i32_e32 v4, 6, v136
	v_lshrrev_b32_e32 v0, 31, v136
	v_add_u32_e32 v0, v4, v0
	v_lshlrev_b32_e32 v3, 10, v136
	s_addc_u32 s11, s72, s29
	s_ashr_i32 s25, s24, 31
	v_ashrrev_i32_e32 v5, 1, v0
	v_and_b32_e32 v0, 0x3fffffe, v0
	v_and_b32_e32 v6, 0xf000, v3
	v_lshlrev_b32_e32 v139, 10, v4
	s_lshl_b64 s[88:89], s[24:25], 12
	v_lshlrev_b32_e32 v7, 4, v136
	v_sub_u32_e32 v0, v4, v0
	v_lshl_or_b32 v3, v5, 16, v6
	v_add_u32_e32 v140, 0x10000, v139
	s_add_u32 s12, s73, s88
	v_and_b32_e32 v8, 32, v136
	v_and_b32_e32 v2, 48, v7
	v_lshl_add_u32 v0, v0, 6, v3
	v_readfirstlane_b32 s21, v140
	s_addc_u32 s13, s74, s89
	v_bitop3_b32 v0, v2, v0, v8 bitop3:0xde
	s_barrier
	s_cmp_ge_i32 s75, s22
	s_cbranch_scc1 .Lat_gu_top_pf
	s_waitcnt vmcnt(0)
	s_branch .Lat_gu_top_j
.Lat_gu_top_pf:
	s_waitcnt vmcnt(8)
.Lat_gu_top_j:
	s_mov_b32 m0, s21
	v_add_u32_e32 v141, 0x12000, v139
	v_lshl_add_u64 v[2:3], s[12:13], 0, v[0:1]
	s_cbranch_scc1 .Lat_gu_sk0
	global_load_lds_dwordx4 v0, s[12:13]
.Lat_gu_sk0:
	v_readfirstlane_b32 s12, v141
	v_lshl_add_u64 v[10:11], v[2:3], 0, s[40:41]
	s_mov_b32 m0, s12
	v_readfirstlane_b32 s12, v139
	s_cbranch_scc1 .Lat_gu_sk1
	global_load_lds_dwordx4 v[10:11], off
.Lat_gu_sk1:
	s_mov_b32 m0, s12
	v_add_u32_e32 v142, 0x2000, v139
	v_lshl_add_u64 v[130:131], s[10:11], 0, v[0:1]
	s_cbranch_scc1 .Lat_gu_sk2
	global_load_lds_dwordx4 v0, s[10:11]
.Lat_gu_sk2:
	v_readfirstlane_b32 s10, v142
	v_add_u32_e32 v143, 0x14000, v139
	v_lshl_add_u64 v[10:11], v[130:131], 0, s[40:41]
	s_mov_b32 m0, s10
	v_readfirstlane_b32 s10, v143
	v_add_u32_e32 v144, 0x16000, v139
	s_cbranch_scc1 .Lat_gu_sk3
	global_load_lds_dwordx4 v[10:11], off
.Lat_gu_sk3:
	v_lshl_add_u64 v[10:11], v[2:3], 0, s[42:43]
	s_mov_b32 m0, s10
	v_readfirstlane_b32 s10, v144
	v_add_u32_e32 v145, 0x4000, v139
	s_cbranch_scc1 .Lat_gu_sk4
	global_load_lds_dwordx4 v[10:11], off
.Lat_gu_sk4:
	v_lshl_add_u64 v[10:11], v[2:3], 0, s[44:45]
	s_mov_b32 m0, s10
	v_readfirstlane_b32 s10, v145
	v_add_u32_e32 v146, 0x6000, v139
	s_cbranch_scc1 .Lat_gu_sk5
	global_load_lds_dwordx4 v[10:11], off
.Lat_gu_sk5:
	v_lshl_add_u64 v[10:11], v[130:131], 0, s[42:43]
	s_mov_b32 m0, s10
	v_readfirstlane_b32 s10, v146
	s_cbranch_scc1 .Lat_gu_sk6
	global_load_lds_dwordx4 v[10:11], off
.Lat_gu_sk6:
	v_lshl_add_u64 v[10:11], v[130:131], 0, s[44:45]
	s_mov_b32 m0, s10
	v_ashrrev_i32_e32 v9, 8, v136
	s_cbranch_scc1 .Lat_gu_sk7
	global_load_lds_dwordx4 v[10:11], off
.Lat_gu_sk7:
	v_cmp_eq_u32_e64 s[12:13], 1, v9
	s_and_saveexec_b64 s[10:11], s[12:13]
	s_cbranch_execz .LBB0_904
	s_barrier
